# strategy 4: one static s_setprio 1 for waves 4-7 at kernel entry, no per-segment flips (base v12)
# baseline (speedup 1.0000x reference)
_Z8mega_fwd4Args:
	s_load_dword s93, s[0:1], 0x98
	s_load_dwordx4 s[84:87], s[0:1], 0x80
	s_load_dwordx2 s[94:95], s[0:1], 0x90
	s_add_u32 s4, s0, 0x90
	s_addc_u32 s5, s1, 0
	v_and_b32_e32 v152, 0x3ff, v0
	s_nop 0
	v_readfirstlane_b32 s98, v152
	s_nop 3
	s_cmpk_lt_u32 s98, 0x100
	s_cbranch_scc1 .Lprio_done
	s_setprio 1
.Lprio_done:
	s_mov_b32 s47, s2
	v_writelane_b32 v247, s4, 0
	v_cmp_gt_u32_e32 vcc, 4, v152
	s_nop 0
	v_writelane_b32 v247, s5, 1
	s_and_saveexec_b64 s[4:5], vcc
	v_lshl_add_u32 v1, v152, 2, 0
	v_add_u32_e32 v1, 0x24000, v1
	v_mov_b32_e32 v2, 0
	ds_write_b32 v1, v2
	s_or_b64 exec, exec, s[4:5]
	s_load_dwordx16 s[16:31], s[0:1], 0x0
	s_waitcnt lgkmcnt(0)
	s_add_u32 s8, s84, 0x2ab0000
	s_addc_u32 s9, s85, 0
	s_barrier
	s_getreg_b32 s3, hwreg(HW_REG_XCC_ID, 0, 4)
	s_cmp_lg_u32 s47, 0
	s_mov_b32 s6, 0
	s_cbranch_scc1 .LBB0_10
	v_sub_u32_e32 v1, 0xd7f, v152
	v_lshrrev_b32_e32 v2, 9, v1
	v_add_u32_e32 v1, 2, v2
	v_add_u32_e32 v153, 0x200, v152
	v_and_b32_e32 v3, 14, v1
	v_mov_b32_e32 v1, v2
	s_mov_b64 s[10:11], 0
	s_mov_b32 s7, 1
	v_mov_b32_e32 v5, 0
	s_mov_b32 s12, s6
	v_mov_b64_e32 v[6:7], v[152:153]
	s_branch .LBB0_5
